# norm phases: w_norm loads issued together (phase A: hoisted out of the row loop; norm2: issued before the reduction) instead of one load+wait per store
# speedup vs baseline: 1.0089x; 1.0009x over previous
; __device__ __forceinline__ int opaque_tid() { int t = threadIdx.x; asm volatile("" : "+v"(t)); return t; }
; __device__ __forceinline__ unsigned cvt_pk_bf16(float lo, float hi) { unsigned r; asm volatile("v_cvt_pk_bf16_f32 %0, %1, %2" : "=v"(r) : "v"(lo), "v"(hi)); return r; }
; __device__ __forceinline__ void phase_norm(const Params& P, int mode, const bf16_t* src, const float* w_add, const float* w_norm, bf16_t* hbuf, bf16_t* xsb, const float* part, int pieces) {
;     const int tid_ = opaque_tid(); const int lane = tid_ & 63, wave = tid_ >> 6; const int gw = blockIdx.x * 8 + wave, NGW = gridDim.x * 8;
;     for (int m = gw; m < MP; m += NGW) {
;         const int b = m / TP, tp = m - b * TP;
;         u32x2* hrow = (u32x2*)(hbuf + (size_t)m * D) + lane;
;     ...
; #pragma unroll
;         for (int j = 0; j < 8; ++j) { const f32x4 w = ((const f32x4*)w_norm)[lane + 64 * j]; const f32x4 o = v[j] * r * w;
;             hrow[64 * j] = (u32x2){cvt_pk_bf16(o.x, o.y), cvt_pk_bf16(o.z, o.w)}; }
.LBB0_23:
	s_xor_b64 s[0:1], s[0:1], -1
	v_mov_b32_e32 v0, v163
	v_mov_b32_e32 v2, v162
	v_writelane_b32 v254, s0, 51
	s_mov_b32 s29, s69
	v_readfirstlane_b32 s5, v0
	v_writelane_b32 v254, s1, 52
	v_mov_b32_e32 v0, v1
	v_writelane_b32 v254, s28, 53
	v_readfirstlane_b32 s14, v0
	s_lshl_b64 s[0:1], s[28:29], 13
	v_writelane_b32 v254, s29, 54
	v_mov_b32_e32 v0, v208
	v_readfirstlane_b32 s4, v2
	v_writelane_b32 v254, s0, 55
	s_nop 0
	v_ashrrev_i32_e32 v2, 6, v0
	v_writelane_b32 v254, s1, 56
	v_add_u32_e32 v66, s51, v2
	s_movk_i32 s0, 0x4100
	v_cmp_gt_i32_e32 vcc, s0, v66
	s_and_saveexec_b64 s[0:1], vcc
	s_cbranch_execz .LBB0_48
	s_ashr_i32 s15, s14, 31
	s_lshl_b64 s[14:15], s[14:15], 3
	v_readlane_b32 s16, v254, 30
	v_readlane_b32 s17, v254, 31
	s_add_u32 s14, s16, s14
	s_addc_u32 s15, s17, s15
	s_load_dwordx2 s[14:15], s[14:15], 0x18
	v_readlane_b32 s16, v254, 55
	v_readlane_b32 s17, v254, 56
	s_lshl_b64 s[16:17], s[16:17], 2
	v_and_b32_e32 v4, 63, v0
	s_waitcnt lgkmcnt(0)
	s_add_u32 s16, s14, s16
	v_lshlrev_b32_e32 v0, 3, v4
	s_addc_u32 s17, s15, s17
	v_lshl_add_u64 v[6:7], s[4:5], 0, v[0:1]
	s_add_u32 s14, s14, 0x6000
	v_lshlrev_b32_e32 v0, 4, v4
	s_addc_u32 s15, s15, 0
	v_or_b32_e32 v8, 0x400, v0
	v_mov_b32_e32 v9, v1
	v_lshl_add_u64 v[76:77], s[14:15], 0, v[8:9]
	v_or_b32_e32 v8, 0x800, v0
	v_lshl_add_u64 v[78:79], s[14:15], 0, v[8:9]
	v_or_b32_e32 v8, 0xc00, v0
	s_mov_b64 s[18:19], 0x4800000
	v_lshl_add_u64 v[80:81], s[14:15], 0, v[8:9]
	v_or_b32_e32 v8, 0x1000, v0
	v_or_b32_e32 v10, 0x1400, v0
	v_mov_b32_e32 v11, v1
	v_or_b32_e32 v12, 0x1800, v0
	v_mov_b32_e32 v13, v1
	v_or_b32_e32 v14, 0x1c00, v0
	v_mov_b32_e32 v15, v1
	v_lshl_add_u64 v[68:69], v[6:7], 0, s[18:19]
	v_lshl_add_u64 v[70:71], s[14:15], 0, v[0:1]
	s_mov_b64 s[18:19], 0x2ba00000
	v_lshl_add_u64 v[82:83], s[14:15], 0, v[8:9]
	v_lshl_add_u64 v[84:85], s[14:15], 0, v[10:11]
	v_lshl_add_u64 v[86:87], s[14:15], 0, v[12:13]
	v_lshl_add_u64 v[88:89], s[14:15], 0, v[14:15]
	s_mov_b64 s[14:15], 0x8900000
	v_lshl_add_u64 v[100:101], s[4:5], 0, v[0:1]
	v_readlane_b32 s4, v254, 12
	v_lshl_add_u64 v[72:73], s[16:17], 0, v[0:1]
	v_lshl_add_u64 v[74:75], v[6:7], 0, s[18:19]
	v_lshl_add_u64 v[90:91], s[16:17], 0, v[8:9]
	v_lshl_add_u64 v[92:93], s[16:17], 0, v[10:11]
	v_lshl_add_u64 v[94:95], s[16:17], 0, v[12:13]
	v_lshl_add_u64 v[96:97], s[16:17], 0, v[14:15]
	v_lshl_add_u64 v[98:99], v[6:7], 0, s[14:15]
	v_add_u32_e32 v102, s4, v2
	s_mov_b64 s[4:5], 0
	v_lshlrev_b32_e32 v104, 4, v4
	global_load_dwordx4 v[166:169], v[72:73], off
	global_load_dwordx4 v[170:173], v[72:73], off offset:1024
	global_load_dwordx4 v[174:177], v[72:73], off offset:2048
	global_load_dwordx4 v[178:181], v[72:73], off offset:3072
	global_load_dwordx4 v[182:185], v[90:91], off
	global_load_dwordx4 v[186:189], v[92:93], off
	global_load_dwordx4 v[190:193], v[94:95], off
	global_load_dwordx4 v[194:197], v[96:97], off
	s_branch .LBB0_26

; __device__ __forceinline__ unsigned cvt_pk_bf16(float lo, float hi) { unsigned r; asm volatile("v_cvt_pk_bf16_f32 %0, %1, %2" : "=v"(r) : "v"(lo), "v"(hi)); return r; }
; __device__ __forceinline__ void phase_norm(const Params& P, int mode, const bf16_t* src, const float* w_add, const float* w_norm, bf16_t* hbuf, bf16_t* xsb, const float* part, int pieces) {
;     ...
;         float ss = 0.f;
; #pragma unroll
;         for (int j = 0; j < 8; ++j) ss += (v[j].x * v[j].x + v[j].y * v[j].y) + (v[j].z * v[j].z + v[j].w * v[j].w);
;         const float r = rsqrtf(wave_sum(ss) * (1.0f / D) + 1e-6f);
; #pragma unroll
;         for (int j = 0; j < 8; ++j) { const f32x4 w = ((const f32x4*)w_norm)[lane + 64 * j]; const f32x4 o = v[j] * r * w;
;             hrow[64 * j] = (u32x2){cvt_pk_bf16(o.x, o.y), cvt_pk_bf16(o.z, o.w)}; }
.LBB0_45:
	s_nop 0
	s_waitcnt vmcnt(7)
	v_mul_f32_e32 v0, v31, v31
	v_mul_f32_e32 v38, v33, v33
	s_waitcnt vmcnt(6)
	v_mul_f32_e32 v39, v27, v27
	v_mul_f32_e32 v40, v29, v29
	s_waitcnt vmcnt(5)
	v_mul_f32_e32 v41, v23, v23
	v_mul_f32_e32 v42, v25, v25
	v_fmac_f32_e32 v0, v30, v30
	v_fmac_f32_e32 v38, v32, v32
	v_fmac_f32_e32 v39, v26, v26
	v_fmac_f32_e32 v40, v28, v28
	s_waitcnt vmcnt(4)
	v_mul_f32_e32 v43, v19, v19
	v_mul_f32_e32 v44, v21, v21
	v_fmac_f32_e32 v41, v22, v22
	v_fmac_f32_e32 v42, v24, v24
	v_add_f32_e32 v0, v0, v38
	v_add_f32_e32 v38, v39, v40
	s_waitcnt vmcnt(3)
	v_mul_f32_e32 v45, v15, v15
	v_mul_f32_e32 v46, v17, v17
	v_fmac_f32_e32 v43, v18, v18
	v_fmac_f32_e32 v44, v20, v20
	v_add_f32_e32 v39, v41, v42
	v_add_f32_e32 v0, v0, v38
	s_waitcnt vmcnt(2)
	v_mul_f32_e32 v47, v11, v11
	v_mul_f32_e32 v48, v13, v13
	v_fmac_f32_e32 v45, v14, v14
	v_fmac_f32_e32 v46, v16, v16
	v_add_f32_e32 v40, v43, v44
	v_add_f32_e32 v0, v39, v0
	s_waitcnt vmcnt(1)
	v_mul_f32_e32 v49, v7, v7
	v_mul_f32_e32 v50, v9, v9
	v_fmac_f32_e32 v47, v10, v10
	v_fmac_f32_e32 v48, v12, v12
	v_add_f32_e32 v41, v45, v46
	v_add_f32_e32 v0, v40, v0
	s_waitcnt vmcnt(0)
	v_mul_f32_e32 v51, v3, v3
	v_mul_f32_e32 v52, v5, v5
	v_fmac_f32_e32 v49, v6, v6
	v_fmac_f32_e32 v50, v8, v8
	v_add_f32_e32 v42, v47, v48
	v_add_f32_e32 v0, v41, v0
	v_fmac_f32_e32 v51, v2, v2
	v_fmac_f32_e32 v52, v4, v4
	v_add_f32_e32 v43, v49, v50
	v_add_f32_e32 v0, v42, v0
	v_add_f32_e32 v44, v51, v52
	v_add_f32_e32 v0, v43, v0
	v_add_f32_e32 v0, v44, v0
	s_mov_b32 s16, 0x800000
	s_nop 0
	v_add_f32_dpp v0, v0, v0 quad_perm:[1,0,3,2] row_mask:0xf bank_mask:0xf bound_ctrl:1
	s_nop 1
	v_add_f32_dpp v0, v0, v0 quad_perm:[2,3,0,1] row_mask:0xf bank_mask:0xf bound_ctrl:1
	s_nop 1
	v_add_f32_dpp v0, v0, v0 row_ror:4 row_mask:0xf bank_mask:0xf bound_ctrl:1
	s_nop 1
	v_add_f32_dpp v0, v0, v0 row_ror:8 row_mask:0xf bank_mask:0xf bound_ctrl:1
	v_mov_b32_e32 v38, v0
	s_nop 1
	v_permlane16_swap_b32_e32 v0, v38
	v_add_f32_e32 v0, v0, v38
	v_mov_b32_e32 v38, v0
	s_nop 1
	v_permlane32_swap_b32_e32 v0, v38
	v_add_f32_e32 v0, v0, v38
	v_fmamk_f32 v0, v0, 0x3a000000, v209
	v_mul_f32_e32 v38, 0x4b800000, v0
	v_cmp_gt_f32_e32 vcc, s16, v0
	s_nop 1
	v_cndmask_b32_e32 v0, v0, v38, vcc
	v_rsq_f32_e32 v0, v0
	s_nop 0
	v_mul_f32_e32 v38, 0x45800000, v0
	v_cndmask_b32_e32 v0, v0, v38, vcc
	v_pk_mul_f32 v[30:31], v[30:31], v[0:1] op_sel_hi:[1,0]
	v_pk_mul_f32 v[32:33], v[32:33], v[0:1] op_sel_hi:[1,0]
	s_waitcnt vmcnt(0)
	v_pk_mul_f32 v[30:31], v[166:167], v[30:31]
	v_pk_mul_f32 v[32:33], v[168:169], v[32:33]
	v_cvt_pk_bf16_f32 v30, v30, v31
	v_pk_mul_f32 v[26:27], v[26:27], v[0:1] op_sel_hi:[1,0]
	v_cvt_pk_bf16_f32 v31, v32, v33
	global_store_dwordx2 v[106:107], v[30:31], off
	s_nop 0
	v_pk_mul_f32 v[28:29], v[28:29], v[0:1] op_sel_hi:[1,0]
	v_pk_mul_f32 v[22:23], v[22:23], v[0:1] op_sel_hi:[1,0]
	v_pk_mul_f32 v[24:25], v[24:25], v[0:1] op_sel_hi:[1,0]
	v_pk_mul_f32 v[18:19], v[18:19], v[0:1] op_sel_hi:[1,0]
	v_pk_mul_f32 v[20:21], v[20:21], v[0:1] op_sel_hi:[1,0]
	v_pk_mul_f32 v[14:15], v[14:15], v[0:1] op_sel_hi:[1,0]
	v_pk_mul_f32 v[16:17], v[16:17], v[0:1] op_sel_hi:[1,0]
	v_pk_mul_f32 v[10:11], v[10:11], v[0:1] op_sel_hi:[1,0]
	v_pk_mul_f32 v[12:13], v[12:13], v[0:1] op_sel_hi:[1,0]
	v_pk_mul_f32 v[6:7], v[6:7], v[0:1] op_sel_hi:[1,0]
	v_pk_mul_f32 v[8:9], v[8:9], v[0:1] op_sel_hi:[1,0]
	v_pk_mul_f32 v[2:3], v[2:3], v[0:1] op_sel_hi:[1,0]
	v_pk_mul_f32 v[4:5], v[4:5], v[0:1] op_sel_hi:[1,0]
	s_nop 0
	v_pk_mul_f32 v[26:27], v[170:171], v[26:27]
	v_pk_mul_f32 v[28:29], v[172:173], v[28:29]
	v_cvt_pk_bf16_f32 v26, v26, v27
	s_nop 0
	v_cvt_pk_bf16_f32 v27, v28, v29
	global_store_dwordx2 v[106:107], v[26:27], off offset:512
	s_nop 0
	s_nop 0
	v_pk_mul_f32 v[22:23], v[174:175], v[22:23]
	v_pk_mul_f32 v[24:25], v[176:177], v[24:25]
	v_cvt_pk_bf16_f32 v22, v22, v23
	s_nop 0
	v_cvt_pk_bf16_f32 v23, v24, v25
	global_store_dwordx2 v[106:107], v[22:23], off offset:1024
	s_nop 0
	s_nop 0
	v_pk_mul_f32 v[18:19], v[18:19], v[178:179]
	v_pk_mul_f32 v[20:21], v[20:21], v[180:181]
	v_cvt_pk_bf16_f32 v18, v18, v19
	s_nop 0
	v_cvt_pk_bf16_f32 v19, v20, v21
	global_store_dwordx2 v[106:107], v[18:19], off offset:1536
	s_nop 0
	s_nop 0
	v_pk_mul_f32 v[14:15], v[14:15], v[182:183]
	v_pk_mul_f32 v[16:17], v[16:17], v[184:185]
	v_cvt_pk_bf16_f32 v14, v14, v15
	s_nop 0
	v_cvt_pk_bf16_f32 v15, v16, v17
	global_store_dwordx2 v[106:107], v[14:15], off offset:2048
	s_nop 0
	s_nop 0
	v_pk_mul_f32 v[10:11], v[10:11], v[186:187]
	v_pk_mul_f32 v[12:13], v[12:13], v[188:189]
	v_cvt_pk_bf16_f32 v10, v10, v11
	s_nop 0
	v_cvt_pk_bf16_f32 v11, v12, v13
	global_store_dwordx2 v[106:107], v[10:11], off offset:2560
	s_nop 0
	s_nop 0
	v_pk_mul_f32 v[6:7], v[6:7], v[190:191]
	v_pk_mul_f32 v[8:9], v[8:9], v[192:193]
	v_cvt_pk_bf16_f32 v6, v6, v7
	s_nop 0
	v_cvt_pk_bf16_f32 v7, v8, v9
	global_store_dwordx2 v[106:107], v[6:7], off offset:3072
	s_nop 0
	s_nop 0
	v_pk_mul_f32 v[2:3], v[2:3], v[194:195]
	v_pk_mul_f32 v[4:5], v[4:5], v[196:197]
	v_cvt_pk_bf16_f32 v2, v2, v3
	s_nop 0
	v_cvt_pk_bf16_f32 v3, v4, v5

; __device__ __forceinline__ void phase_norm(const Params& P, int mode, const bf16_t* src, const float* w_add, const float* w_norm, bf16_t* hbuf, bf16_t* xsb, const float* part, int pieces) {
;     ...
; #pragma unroll
;             for (int j = 0; j < 8; ++j) ss += (s[j].x * s[j].x + s[j].y * s[j].y) + (s[j].z * s[j].z + s[j].w * s[j].w);
;             const float r = rsqrtf(wave_sum(ss) * (1.0f / D) + 1e-6f);
; #pragma unroll
;             for (int j = 0; j < 8; ++j) { const f32x4 w = ((const f32x4*)w_add)[lane + 64 * j]; v[j] += s[j] * r * w; }
.LBB0_1570:
	s_or_b64 exec, exec, s[16:17]
	global_load_dwordx4 v[116:119], v[70:71], off
	v_mul_f32_e32 v0, v63, v63
	v_mul_f32_e32 v67, v65, v65
	v_fmac_f32_e32 v0, v62, v62
	v_fmac_f32_e32 v67, v64, v64
	v_add_f32_e32 v0, v0, v67
	v_mul_f32_e32 v67, v59, v59
	v_mul_f32_e32 v109, v61, v61
	v_fmac_f32_e32 v67, v58, v58
	v_fmac_f32_e32 v109, v60, v60
	v_add_f32_e32 v67, v67, v109
	v_add_f32_e32 v0, v67, v0
	v_mul_f32_e32 v67, v55, v55
	v_mul_f32_e32 v109, v57, v57
	v_fmac_f32_e32 v67, v54, v54
	v_fmac_f32_e32 v109, v56, v56
	v_add_f32_e32 v67, v67, v109
	v_add_f32_e32 v0, v67, v0
	v_mul_f32_e32 v67, v51, v51
	v_mul_f32_e32 v109, v53, v53
	v_fmac_f32_e32 v67, v50, v50
	v_fmac_f32_e32 v109, v52, v52
	v_add_f32_e32 v67, v67, v109
	v_add_f32_e32 v0, v67, v0
	v_mul_f32_e32 v67, v47, v47
	v_mul_f32_e32 v109, v49, v49
	v_fmac_f32_e32 v67, v46, v46
	v_fmac_f32_e32 v109, v48, v48
	v_add_f32_e32 v67, v67, v109
	v_add_f32_e32 v0, v67, v0
	v_mul_f32_e32 v67, v43, v43
	v_mul_f32_e32 v109, v45, v45
	v_fmac_f32_e32 v67, v42, v42
	v_fmac_f32_e32 v109, v44, v44
	v_add_f32_e32 v67, v67, v109
	v_add_f32_e32 v0, v67, v0
	v_mul_f32_e32 v67, v39, v39
	v_mul_f32_e32 v109, v41, v41
	v_fmac_f32_e32 v67, v38, v38
	v_fmac_f32_e32 v109, v40, v40
	v_add_f32_e32 v67, v67, v109
	v_add_f32_e32 v0, v67, v0
	v_mul_f32_e32 v67, v35, v35
	v_mul_f32_e32 v109, v37, v37
	v_fmac_f32_e32 v67, v34, v34
	v_fmac_f32_e32 v109, v36, v36
	v_add_f32_e32 v67, v67, v109
	v_add_f32_e32 v0, v67, v0
	s_mov_b32 s16, 0x800000
	s_nop 0
	v_add_f32_dpp v0, v0, v0 quad_perm:[1,0,3,2] row_mask:0xf bank_mask:0xf bound_ctrl:1
	s_nop 1
	v_add_f32_dpp v0, v0, v0 quad_perm:[2,3,0,1] row_mask:0xf bank_mask:0xf bound_ctrl:1
	s_nop 1
	v_add_f32_dpp v0, v0, v0 row_ror:4 row_mask:0xf bank_mask:0xf bound_ctrl:1
	s_nop 1
	v_add_f32_dpp v0, v0, v0 row_ror:8 row_mask:0xf bank_mask:0xf bound_ctrl:1
	v_mov_b32_e32 v67, v0
	s_nop 1
	v_permlane16_swap_b32_e32 v0, v67
	v_add_f32_e32 v0, v0, v67
	v_mov_b32_e32 v67, v0
	s_nop 1
	v_permlane32_swap_b32_e32 v0, v67
	v_add_f32_e32 v0, v0, v67
	v_fmamk_f32 v0, v0, 0x3a000000, v209
	v_cmp_gt_f32_e32 vcc, s16, v0
	v_mul_f32_e32 v67, 0x4b800000, v0
	s_nop 0
	v_cndmask_b32_e32 v0, v0, v67, vcc
	v_rsq_f32_e32 v0, v0
	s_nop 0
	v_mul_f32_e32 v67, 0x45800000, v0
	v_cndmask_b32_e32 v0, v0, v67, vcc
	v_pk_mul_f32 v[64:65], v[64:65], v[0:1] op_sel_hi:[1,0]
	v_pk_mul_f32 v[62:63], v[62:63], v[0:1] op_sel_hi:[1,0]
	s_waitcnt vmcnt(0)
	v_pk_fma_f32 v[32:33], v[118:119], v[64:65], v[32:33]
	v_pk_fma_f32 v[30:31], v[116:117], v[62:63], v[30:31]
	global_load_dwordx4 v[62:65], v[76:77], off
	v_pk_mul_f32 v[60:61], v[60:61], v[0:1] op_sel_hi:[1,0]
	v_pk_mul_f32 v[58:59], v[58:59], v[0:1] op_sel_hi:[1,0]
	v_pk_mul_f32 v[56:57], v[56:57], v[0:1] op_sel_hi:[1,0]
	v_pk_mul_f32 v[54:55], v[54:55], v[0:1] op_sel_hi:[1,0]
	v_pk_mul_f32 v[52:53], v[52:53], v[0:1] op_sel_hi:[1,0]
	v_pk_mul_f32 v[50:51], v[50:51], v[0:1] op_sel_hi:[1,0]
	v_pk_mul_f32 v[48:49], v[48:49], v[0:1] op_sel_hi:[1,0]
	v_pk_mul_f32 v[46:47], v[46:47], v[0:1] op_sel_hi:[1,0]
	v_pk_mul_f32 v[44:45], v[44:45], v[0:1] op_sel_hi:[1,0]
	v_pk_mul_f32 v[42:43], v[42:43], v[0:1] op_sel_hi:[1,0]
	v_pk_mul_f32 v[40:41], v[40:41], v[0:1] op_sel_hi:[1,0]
	v_pk_mul_f32 v[38:39], v[38:39], v[0:1] op_sel_hi:[1,0]
	v_pk_mul_f32 v[34:35], v[34:35], v[0:1] op_sel_hi:[1,0]
	v_pk_mul_f32 v[36:37], v[36:37], v[0:1] op_sel_hi:[1,0]
	v_mul_f32_e32 v0, v31, v31
	v_fmac_f32_e32 v0, v30, v30
	s_waitcnt vmcnt(0)
	v_pk_fma_f32 v[26:27], v[62:63], v[58:59], v[26:27]
	v_pk_fma_f32 v[28:29], v[64:65], v[60:61], v[28:29]
	global_load_dwordx4 v[58:61], v[78:79], off
	s_waitcnt vmcnt(0)
	v_pk_fma_f32 v[22:23], v[58:59], v[54:55], v[22:23]
	v_pk_fma_f32 v[24:25], v[60:61], v[56:57], v[24:25]
	global_load_dwordx4 v[54:57], v[80:81], off
	s_waitcnt vmcnt(0)
	v_pk_fma_f32 v[18:19], v[54:55], v[50:51], v[18:19]
	v_pk_fma_f32 v[20:21], v[56:57], v[52:53], v[20:21]
	global_load_dwordx4 v[50:53], v[82:83], off
	s_waitcnt vmcnt(0)
	v_pk_fma_f32 v[14:15], v[50:51], v[46:47], v[14:15]
	v_pk_fma_f32 v[16:17], v[52:53], v[48:49], v[16:17]
	global_load_dwordx4 v[46:49], v[84:85], off
	s_waitcnt vmcnt(0)
	v_pk_fma_f32 v[10:11], v[46:47], v[42:43], v[10:11]
	v_pk_fma_f32 v[12:13], v[48:49], v[44:45], v[12:13]
	global_load_dwordx4 v[42:45], v[86:87], off
	s_waitcnt vmcnt(0)
	v_pk_fma_f32 v[38:39], v[42:43], v[38:39], v[6:7]
	v_pk_fma_f32 v[40:41], v[44:45], v[40:41], v[8:9]
	global_load_dwordx4 v[6:9], v[88:89], off
	s_waitcnt vmcnt(0)
; __device__ __forceinline__ unsigned cvt_pk_bf16(float lo, float hi) { unsigned r; asm volatile("v_cvt_pk_bf16_f32 %0, %1, %2" : "=v"(r) : "v"(lo), "v"(hi)); return r; }
; __device__ __forceinline__ void phase_norm(const Params& P, int mode, const bf16_t* src, const float* w_add, const float* w_norm, bf16_t* hbuf, bf16_t* xsb, const float* part, int pieces) {
;     ...
; #pragma unroll
;             for (int j = 0; j < 8; ++j) ((u32x2*)(xsb + (size_t)m * D))[lane + 64 * j] = (u32x2){cvt_pk_bf16(v[j].x, v[j].y), cvt_pk_bf16(v[j].z, v[j].w)};
;         }
;         float ss = 0.f;
; #pragma unroll
;         for (int j = 0; j < 8; ++j) ss += (v[j].x * v[j].x + v[j].y * v[j].y) + (v[j].z * v[j].z + v[j].w * v[j].w);
;         const float r = rsqrtf(wave_sum(ss) * (1.0f / D) + 1e-6f);
; #pragma unroll
;         for (int j = 0; j < 8; ++j) { const f32x4 w = ((const f32x4*)w_norm)[lane + 64 * j]; const f32x4 o = v[j] * r * w;
;             hrow[64 * j] = (u32x2){cvt_pk_bf16(o.x, o.y), cvt_pk_bf16(o.z, o.w)}; }
	v_pk_fma_f32 v[6:7], v[6:7], v[34:35], v[2:3]
	v_cvt_pk_bf16_f32 v2, v30, v31
	v_cvt_pk_bf16_f32 v3, v32, v33
	global_store_dwordx2 v[114:115], v[2:3], off
	v_cvt_pk_bf16_f32 v2, v26, v27
	v_cvt_pk_bf16_f32 v3, v28, v29
	global_store_dwordx2 v[114:115], v[2:3], off offset:512
	v_cvt_pk_bf16_f32 v2, v22, v23
	v_cvt_pk_bf16_f32 v3, v24, v25
	global_store_dwordx2 v[114:115], v[2:3], off offset:1024
	v_cvt_pk_bf16_f32 v2, v18, v19
	v_cvt_pk_bf16_f32 v3, v20, v21
	global_store_dwordx2 v[114:115], v[2:3], off offset:1536
	v_cvt_pk_bf16_f32 v2, v14, v15
	v_cvt_pk_bf16_f32 v3, v16, v17
	global_store_dwordx2 v[114:115], v[2:3], off offset:2048
	v_cvt_pk_bf16_f32 v2, v10, v11
	v_cvt_pk_bf16_f32 v3, v12, v13
	global_store_dwordx2 v[114:115], v[2:3], off offset:2560
	v_cvt_pk_bf16_f32 v2, v38, v39
	v_cvt_pk_bf16_f32 v3, v40, v41
	global_store_dwordx2 v[114:115], v[2:3], off offset:3072
	v_cvt_pk_bf16_f32 v2, v6, v7
	v_pk_fma_f32 v[8:9], v[8:9], v[36:37], v[4:5]
	s_nop 0
	v_cvt_pk_bf16_f32 v3, v8, v9
	global_store_dwordx2 v[114:115], v[2:3], off offset:3584
	v_mul_f32_e32 v2, v33, v33
	v_fmac_f32_e32 v2, v32, v32
	v_add_f32_e32 v0, v0, v2
	v_mul_f32_e32 v2, v27, v27
	v_mul_f32_e32 v3, v29, v29
	v_fmac_f32_e32 v2, v26, v26
	v_fmac_f32_e32 v3, v28, v28
	v_add_f32_e32 v2, v2, v3
	v_add_f32_e32 v0, v0, v2
	v_mul_f32_e32 v2, v23, v23
	v_mul_f32_e32 v3, v25, v25
	v_fmac_f32_e32 v2, v22, v22
	v_fmac_f32_e32 v3, v24, v24
	v_add_f32_e32 v2, v2, v3
	v_add_f32_e32 v0, v2, v0
	v_mul_f32_e32 v2, v19, v19
	v_mul_f32_e32 v3, v21, v21
	v_fmac_f32_e32 v2, v18, v18
	v_fmac_f32_e32 v3, v20, v20
	v_add_f32_e32 v2, v2, v3
	v_add_f32_e32 v0, v2, v0
	v_mul_f32_e32 v2, v15, v15
	v_mul_f32_e32 v3, v17, v17
	v_fmac_f32_e32 v2, v14, v14
	v_fmac_f32_e32 v3, v16, v16
	v_add_f32_e32 v2, v2, v3
	v_add_f32_e32 v0, v2, v0
	v_mul_f32_e32 v2, v11, v11
	v_mul_f32_e32 v3, v13, v13
	v_fmac_f32_e32 v2, v10, v10
	v_fmac_f32_e32 v3, v12, v12
	global_load_dwordx4 v[134:137], v[72:73], off
	global_load_dwordx4 v[138:141], v[90:91], off
	global_load_dwordx4 v[142:145], v[92:93], off
	global_load_dwordx4 v[146:149], v[94:95], off
	global_load_dwordx4 v[150:153], v[96:97], off
	global_load_dwordx4 v[154:157], v[98:99], off
	global_load_dwordx4 v[166:169], v[100:101], off
	global_load_dwordx4 v[170:173], v[102:103], off
	v_add_f32_e32 v2, v2, v3
	v_add_f32_e32 v0, v2, v0
	v_mul_f32_e32 v2, v39, v39
	v_mul_f32_e32 v3, v41, v41
	v_fmac_f32_e32 v2, v38, v38
	v_fmac_f32_e32 v3, v40, v40
	v_add_f32_e32 v2, v2, v3
	v_add_f32_e32 v0, v2, v0
	v_mul_f32_e32 v2, v7, v7
	v_mul_f32_e32 v3, v9, v9
	v_fmac_f32_e32 v2, v6, v6
	v_fmac_f32_e32 v3, v8, v8
	v_add_f32_e32 v2, v2, v3
	v_add_f32_e32 v0, v2, v0
	s_nop 1
	v_add_f32_dpp v0, v0, v0 quad_perm:[1,0,3,2] row_mask:0xf bank_mask:0xf bound_ctrl:1
	s_nop 1
	v_add_f32_dpp v0, v0, v0 quad_perm:[2,3,0,1] row_mask:0xf bank_mask:0xf bound_ctrl:1
	s_nop 1
	v_add_f32_dpp v0, v0, v0 row_ror:4 row_mask:0xf bank_mask:0xf bound_ctrl:1
	s_nop 1
	v_add_f32_dpp v0, v0, v0 row_ror:8 row_mask:0xf bank_mask:0xf bound_ctrl:1
	v_mov_b32_e32 v2, v0
	s_nop 1
	v_permlane16_swap_b32_e32 v0, v2
	v_add_f32_e32 v0, v0, v2
	v_mov_b32_e32 v2, v0
	s_nop 1
	v_permlane32_swap_b32_e32 v0, v2
	v_add_f32_e32 v0, v0, v2
	v_fmamk_f32 v0, v0, 0x3a000000, v209
	v_cmp_gt_f32_e32 vcc, s16, v0
	v_mul_f32_e32 v2, 0x4b800000, v0
	s_nop 0
	v_cndmask_b32_e32 v0, v0, v2, vcc
	v_rsq_f32_e32 v0, v0
	s_nop 0
	v_mul_f32_e32 v2, 0x45800000, v0
	v_cndmask_b32_e32 v0, v0, v2, vcc
	s_nop 0
	v_pk_mul_f32 v[30:31], v[30:31], v[0:1] op_sel_hi:[1,0]
	v_pk_mul_f32 v[32:33], v[32:33], v[0:1] op_sel_hi:[1,0]
	v_pk_mul_f32 v[26:27], v[26:27], v[0:1] op_sel_hi:[1,0]
	v_pk_mul_f32 v[28:29], v[28:29], v[0:1] op_sel_hi:[1,0]
	v_pk_mul_f32 v[22:23], v[22:23], v[0:1] op_sel_hi:[1,0]
	v_pk_mul_f32 v[24:25], v[24:25], v[0:1] op_sel_hi:[1,0]
	v_pk_mul_f32 v[18:19], v[18:19], v[0:1] op_sel_hi:[1,0]
	v_pk_mul_f32 v[20:21], v[20:21], v[0:1] op_sel_hi:[1,0]
	v_pk_mul_f32 v[14:15], v[14:15], v[0:1] op_sel_hi:[1,0]
	v_pk_mul_f32 v[16:17], v[16:17], v[0:1] op_sel_hi:[1,0]
	v_pk_mul_f32 v[10:11], v[10:11], v[0:1] op_sel_hi:[1,0]
	v_pk_mul_f32 v[12:13], v[12:13], v[0:1] op_sel_hi:[1,0]
	v_pk_mul_f32 v[6:7], v[6:7], v[0:1] op_sel_hi:[1,0]
	v_pk_mul_f32 v[8:9], v[8:9], v[0:1] op_sel_hi:[1,0]
	s_waitcnt vmcnt(0)
	v_pk_mul_f32 v[2:3], v[134:135], v[30:31]
	v_pk_mul_f32 v[4:5], v[136:137], v[32:33]
	v_cvt_pk_bf16_f32 v2, v2, v3
	s_nop 0
	v_cvt_pk_bf16_f32 v3, v4, v5
	global_store_dwordx2 v[112:113], v[2:3], off
	s_nop 0
	s_nop 0
	v_pk_mul_f32 v[2:3], v[138:139], v[26:27]
	v_pk_mul_f32 v[4:5], v[140:141], v[28:29]
	v_cvt_pk_bf16_f32 v2, v2, v3
	s_nop 0
	v_cvt_pk_bf16_f32 v3, v4, v5
	global_store_dwordx2 v[112:113], v[2:3], off offset:512
	s_nop 0
	s_nop 0
	v_pk_mul_f32 v[2:3], v[142:143], v[22:23]
	v_pk_mul_f32 v[4:5], v[144:145], v[24:25]
	v_cvt_pk_bf16_f32 v2, v2, v3
	s_nop 0
	v_cvt_pk_bf16_f32 v3, v4, v5
	global_store_dwordx2 v[112:113], v[2:3], off offset:1024
	s_nop 0
	s_nop 0
	v_pk_mul_f32 v[2:3], v[18:19], v[146:147]
	v_pk_mul_f32 v[4:5], v[20:21], v[148:149]
	v_cvt_pk_bf16_f32 v2, v2, v3
	s_nop 0
	v_cvt_pk_bf16_f32 v3, v4, v5
	global_store_dwordx2 v[112:113], v[2:3], off offset:1536
	s_nop 0
	s_nop 0
	v_pk_mul_f32 v[2:3], v[14:15], v[150:151]
	v_pk_mul_f32 v[4:5], v[16:17], v[152:153]
	v_cvt_pk_bf16_f32 v2, v2, v3
	s_nop 0
	v_cvt_pk_bf16_f32 v3, v4, v5
	global_store_dwordx2 v[112:113], v[2:3], off offset:2048
	s_nop 0
	s_nop 0
	v_pk_mul_f32 v[2:3], v[10:11], v[154:155]
	v_pk_mul_f32 v[4:5], v[12:13], v[156:157]
	v_cvt_pk_bf16_f32 v2, v2, v3
	v_pk_mul_f32 v[10:11], v[38:39], v[0:1] op_sel_hi:[1,0]
	v_cvt_pk_bf16_f32 v3, v4, v5
	global_store_dwordx2 v[112:113], v[2:3], off offset:2560
	s_nop 0
	v_pk_mul_f32 v[12:13], v[40:41], v[0:1] op_sel_hi:[1,0]
	s_nop 0
	v_pk_mul_f32 v[2:3], v[10:11], v[166:167]
	v_pk_mul_f32 v[4:5], v[12:13], v[168:169]
	v_cvt_pk_bf16_f32 v2, v2, v3
	s_nop 0
	v_cvt_pk_bf16_f32 v3, v4, v5
	global_store_dwordx2 v[112:113], v[2:3], off offset:3072
	s_nop 0
	s_nop 0
	v_pk_mul_f32 v[2:3], v[6:7], v[170:171]
	v_pk_mul_f32 v[4:5], v[8:9], v[172:173]
	v_cvt_pk_bf16_f32 v2, v2, v3
	s_nop 0
	v_cvt_pk_bf16_f32 v3, v4, v5
